# norm0 phase: three rows in flight per wave instead of two (third register buffer)
# baseline (speedup 1.0000x reference)
.LBB0_48:
	v_readfirstlane_b32 s52, v70
	v_readfirstlane_b32 s53, v71
	v_readfirstlane_b32 s54, v34
	v_readfirstlane_b32 s55, v35
	s_add_u32 s56, s22, 0x5a00000
	s_addc_u32 s57, s23, 0
	s_lshl_b32 s31, s24, 11
	s_add_u32 s56, s56, s31
	s_addc_u32 s57, s57, 0
	s_lshl_b32 s48, s24, 12
	v_lshlrev_b32_e32 v82, 5, v244
	v_lshlrev_b32_e32 v83, 4, v244
	global_load_dwordx4 v[84:87], v82, s[52:53]
	global_load_dwordx4 v[88:91], v82, s[52:53] offset:16
	global_load_dwordx4 v[92:95], v82, s[52:53] offset:2048
	global_load_dwordx4 v[96:99], v82, s[52:53] offset:2064
	s_add_u32 s40, s97, s48
	s_addc_u32 s41, s3, 0
	s_add_u32 s42, s54, 0x0
	s_addc_u32 s43, s55, 0
	s_add_u32 s44, s42, 0x1000
	s_addc_u32 s45, s43, 0
	global_load_dwordx4 v[0:3], v82, s[40:41]
	global_load_dwordx4 v[4:7], v82, s[40:41] offset:16
	global_load_dwordx4 v[8:11], v82, s[40:41] offset:2048
	global_load_dwordx4 v[12:15], v82, s[40:41] offset:2064
	global_load_dwordx4 v[16:19], v82, s[44:45]
	global_load_dwordx4 v[20:23], v82, s[44:45] offset:16
	global_load_dwordx4 v[24:27], v82, s[44:45] offset:2048
	global_load_dwordx4 v[28:31], v82, s[44:45] offset:2064
	global_load_dwordx4 v[38:41], v82, s[42:43]
	global_load_dwordx4 v[42:45], v82, s[42:43] offset:16
	global_load_dwordx4 v[46:49], v82, s[42:43] offset:2048
	global_load_dwordx4 v[50:53], v82, s[42:43] offset:2064
	s_add_u32 s40, s97, s48
	s_addc_u32 s41, s3, 0
	s_add_u32 s40, s40, 0x800000
	s_addc_u32 s41, s41, 0
	s_add_u32 s42, s54, 0x9000
	s_addc_u32 s43, s55, 0
	s_add_u32 s44, s42, 0x1000
	s_addc_u32 s45, s43, 0
	global_load_dwordx4 v[100:103], v82, s[40:41]
	global_load_dwordx4 v[104:107], v82, s[40:41] offset:16
	global_load_dwordx4 v[108:111], v82, s[40:41] offset:2048
	global_load_dwordx4 v[112:115], v82, s[40:41] offset:2064
	global_load_dwordx4 v[116:119], v82, s[44:45]
	global_load_dwordx4 v[120:123], v82, s[44:45] offset:16
	global_load_dwordx4 v[124:127], v82, s[44:45] offset:2048
	global_load_dwordx4 v[128:131], v82, s[44:45] offset:2064
	global_load_dwordx4 v[132:135], v82, s[42:43]
	global_load_dwordx4 v[136:139], v82, s[42:43] offset:16
	global_load_dwordx4 v[140:143], v82, s[42:43] offset:2048
	global_load_dwordx4 v[144:147], v82, s[42:43] offset:2064
	s_add_u32 s40, s97, s48
	s_addc_u32 s41, s3, 0
	s_add_u32 s40, s40, 0x1000000
	s_addc_u32 s41, s41, 0
	s_add_u32 s42, s54, 0x12000
	s_addc_u32 s43, s55, 0
	s_add_u32 s44, s42, 0x1000
	s_addc_u32 s45, s43, 0
	global_load_dwordx4 v[148:151], v82, s[40:41]
	global_load_dwordx4 v[152:155], v82, s[40:41] offset:16
	global_load_dwordx4 v[156:159], v82, s[40:41] offset:2048
	global_load_dwordx4 v[160:163], v82, s[40:41] offset:2064
	global_load_dwordx4 v[200:203], v82, s[44:45]
	global_load_dwordx4 v[204:207], v82, s[44:45] offset:16
	global_load_dwordx4 v[208:211], v82, s[44:45] offset:2048
	global_load_dwordx4 v[212:215], v82, s[44:45] offset:2064
	global_load_dwordx4 v[184:187], v82, s[42:43]
	global_load_dwordx4 v[188:191], v82, s[42:43] offset:16
	global_load_dwordx4 v[192:195], v82, s[42:43] offset:2048
	global_load_dwordx4 v[196:199], v82, s[42:43] offset:2064
	s_waitcnt vmcnt(24)
	v_pk_mul_f32 v[54:55], v[0:1], v[0:1]
	v_pk_mul_f32 v[56:57], v[2:3], v[2:3]
	v_pk_fma_f32 v[54:55], v[4:5], v[4:5], v[54:55]
	v_pk_fma_f32 v[56:57], v[6:7], v[6:7], v[56:57]
	v_pk_fma_f32 v[54:55], v[8:9], v[8:9], v[54:55]
	v_pk_fma_f32 v[56:57], v[10:11], v[10:11], v[56:57]
	v_pk_fma_f32 v[54:55], v[12:13], v[12:13], v[54:55]
	v_pk_fma_f32 v[56:57], v[14:15], v[14:15], v[56:57]
	v_pk_add_f32 v[54:55], v[54:55], v[56:57]
	v_pk_fma_f32 v[16:17], v[84:85], v[16:17], v[84:85]
	v_add_f32_e32 v54, v54, v55
	v_pk_fma_f32 v[18:19], v[86:87], v[18:19], v[86:87]
	v_pk_fma_f32 v[20:21], v[88:89], v[20:21], v[88:89]
	v_add_f32_dpp v54, v54, v54 quad_perm:[1,0,3,2] row_mask:0xf bank_mask:0xf
	v_pk_fma_f32 v[22:23], v[90:91], v[22:23], v[90:91]
	v_pk_fma_f32 v[24:25], v[92:93], v[24:25], v[92:93]
	v_add_f32_dpp v54, v54, v54 quad_perm:[2,3,0,1] row_mask:0xf bank_mask:0xf
	v_pk_fma_f32 v[26:27], v[94:95], v[26:27], v[94:95]
	v_pk_fma_f32 v[28:29], v[96:97], v[28:29], v[96:97]
	v_add_f32_dpp v54, v54, v54 row_half_mirror row_mask:0xf bank_mask:0xf
	v_pk_fma_f32 v[30:31], v[98:99], v[30:31], v[98:99]
	s_nop 1
	v_add_f32_dpp v54, v54, v54 row_mirror row_mask:0xf bank_mask:0xf
	s_nop 0
	v_mov_b32_e32 v55, v54
	s_nop 1
	v_permlane16_swap_b32_e32 v54, v55
	s_nop 0
	v_add_f32_e32 v54, v54, v55
	s_nop 0
	v_mov_b32_e32 v55, v54
	s_nop 1
	v_permlane32_swap_b32_e32 v54, v55
	s_nop 0
	v_add_f32_e32 v54, v54, v55
	v_fmamk_f32 v54, v54, 0x3a800000, v227
	v_rsq_f32_e32 v54, v54
	s_nop 1
	v_pk_mul_f32 v[0:1], v[0:1], v[54:55] op_sel_hi:[1,0]
	v_pk_mul_f32 v[2:3], v[2:3], v[54:55] op_sel_hi:[1,0]
	v_pk_mul_f32 v[4:5], v[4:5], v[54:55] op_sel_hi:[1,0]
	v_pk_mul_f32 v[6:7], v[6:7], v[54:55] op_sel_hi:[1,0]
	v_pk_mul_f32 v[8:9], v[8:9], v[54:55] op_sel_hi:[1,0]
	v_pk_mul_f32 v[10:11], v[10:11], v[54:55] op_sel_hi:[1,0]
	v_pk_mul_f32 v[12:13], v[12:13], v[54:55] op_sel_hi:[1,0]
	v_pk_mul_f32 v[14:15], v[14:15], v[54:55] op_sel_hi:[1,0]
	v_pk_fma_f32 v[0:1], v[0:1], v[16:17], v[38:39]
	v_pk_fma_f32 v[2:3], v[2:3], v[18:19], v[40:41]
	v_pk_fma_f32 v[4:5], v[4:5], v[20:21], v[42:43]
	v_pk_fma_f32 v[6:7], v[6:7], v[22:23], v[44:45]
	v_pk_fma_f32 v[8:9], v[8:9], v[24:25], v[46:47]
	v_pk_fma_f32 v[10:11], v[10:11], v[26:27], v[48:49]
	v_pk_fma_f32 v[12:13], v[12:13], v[28:29], v[50:51]
	v_pk_fma_f32 v[14:15], v[14:15], v[30:31], v[52:53]
	v_cvt_pk_bf16_f32 v0, v0, v1
	v_cvt_pk_bf16_f32 v1, v2, v3
	v_cvt_pk_bf16_f32 v2, v4, v5
	v_cvt_pk_bf16_f32 v3, v6, v7
	v_cvt_pk_bf16_f32 v4, v8, v9
	v_cvt_pk_bf16_f32 v5, v10, v11
	v_cvt_pk_bf16_f32 v6, v12, v13
	v_cvt_pk_bf16_f32 v7, v14, v15
	global_store_dwordx4 v83, v[0:3], s[56:57]
	global_store_dwordx4 v83, v[4:7], s[56:57] offset:1024
	s_add_u32 s40, s97, s48
	s_addc_u32 s41, s3, 0
	s_add_u32 s40, s40, 0x1800000
	s_addc_u32 s41, s41, 0
	s_add_u32 s42, s54, 0x1b000
	s_addc_u32 s43, s55, 0
	s_add_u32 s44, s42, 0x1000
	s_addc_u32 s45, s43, 0
	global_load_dwordx4 v[0:3], v82, s[40:41]
	global_load_dwordx4 v[4:7], v82, s[40:41] offset:16
	global_load_dwordx4 v[8:11], v82, s[40:41] offset:2048
	global_load_dwordx4 v[12:15], v82, s[40:41] offset:2064
	global_load_dwordx4 v[16:19], v82, s[44:45]
	global_load_dwordx4 v[20:23], v82, s[44:45] offset:16
	global_load_dwordx4 v[24:27], v82, s[44:45] offset:2048
	global_load_dwordx4 v[28:31], v82, s[44:45] offset:2064
	global_load_dwordx4 v[38:41], v82, s[42:43]
	global_load_dwordx4 v[42:45], v82, s[42:43] offset:16
	global_load_dwordx4 v[46:49], v82, s[42:43] offset:2048
	global_load_dwordx4 v[50:53], v82, s[42:43] offset:2064
	s_waitcnt vmcnt(26)
	v_pk_mul_f32 v[54:55], v[100:101], v[100:101]
	v_pk_mul_f32 v[56:57], v[102:103], v[102:103]
	v_pk_fma_f32 v[54:55], v[104:105], v[104:105], v[54:55]
	v_pk_fma_f32 v[56:57], v[106:107], v[106:107], v[56:57]
	v_pk_fma_f32 v[54:55], v[108:109], v[108:109], v[54:55]
	v_pk_fma_f32 v[56:57], v[110:111], v[110:111], v[56:57]
	v_pk_fma_f32 v[54:55], v[112:113], v[112:113], v[54:55]
	v_pk_fma_f32 v[56:57], v[114:115], v[114:115], v[56:57]
	v_pk_add_f32 v[54:55], v[54:55], v[56:57]
	v_pk_fma_f32 v[116:117], v[84:85], v[116:117], v[84:85]
	v_add_f32_e32 v54, v54, v55
	v_pk_fma_f32 v[118:119], v[86:87], v[118:119], v[86:87]
	v_pk_fma_f32 v[120:121], v[88:89], v[120:121], v[88:89]
	v_add_f32_dpp v54, v54, v54 quad_perm:[1,0,3,2] row_mask:0xf bank_mask:0xf
	v_pk_fma_f32 v[122:123], v[90:91], v[122:123], v[90:91]
	v_pk_fma_f32 v[124:125], v[92:93], v[124:125], v[92:93]
	v_add_f32_dpp v54, v54, v54 quad_perm:[2,3,0,1] row_mask:0xf bank_mask:0xf
	v_pk_fma_f32 v[126:127], v[94:95], v[126:127], v[94:95]
	v_pk_fma_f32 v[128:129], v[96:97], v[128:129], v[96:97]
	v_add_f32_dpp v54, v54, v54 row_half_mirror row_mask:0xf bank_mask:0xf
	v_pk_fma_f32 v[130:131], v[98:99], v[130:131], v[98:99]
	s_nop 1
	v_add_f32_dpp v54, v54, v54 row_mirror row_mask:0xf bank_mask:0xf
	s_nop 0
	v_mov_b32_e32 v55, v54
	s_nop 1
	v_permlane16_swap_b32_e32 v54, v55
	s_nop 0
	v_add_f32_e32 v54, v54, v55
	s_nop 0
	v_mov_b32_e32 v55, v54
	s_nop 1
	v_permlane32_swap_b32_e32 v54, v55
	s_nop 0
	v_add_f32_e32 v54, v54, v55
	v_fmamk_f32 v54, v54, 0x3a800000, v227
	v_rsq_f32_e32 v54, v54
	s_nop 1
	v_pk_mul_f32 v[100:101], v[100:101], v[54:55] op_sel_hi:[1,0]
	v_pk_mul_f32 v[102:103], v[102:103], v[54:55] op_sel_hi:[1,0]
	v_pk_mul_f32 v[104:105], v[104:105], v[54:55] op_sel_hi:[1,0]
	v_pk_mul_f32 v[106:107], v[106:107], v[54:55] op_sel_hi:[1,0]
	v_pk_mul_f32 v[108:109], v[108:109], v[54:55] op_sel_hi:[1,0]
	v_pk_mul_f32 v[110:111], v[110:111], v[54:55] op_sel_hi:[1,0]
	v_pk_mul_f32 v[112:113], v[112:113], v[54:55] op_sel_hi:[1,0]
	v_pk_mul_f32 v[114:115], v[114:115], v[54:55] op_sel_hi:[1,0]
	v_pk_fma_f32 v[100:101], v[100:101], v[116:117], v[132:133]
	v_pk_fma_f32 v[102:103], v[102:103], v[118:119], v[134:135]
	v_pk_fma_f32 v[104:105], v[104:105], v[120:121], v[136:137]
	v_pk_fma_f32 v[106:107], v[106:107], v[122:123], v[138:139]
	v_pk_fma_f32 v[108:109], v[108:109], v[124:125], v[140:141]
	v_pk_fma_f32 v[110:111], v[110:111], v[126:127], v[142:143]
	v_pk_fma_f32 v[112:113], v[112:113], v[128:129], v[144:145]
	v_pk_fma_f32 v[114:115], v[114:115], v[130:131], v[146:147]
	v_cvt_pk_bf16_f32 v100, v100, v101
	v_cvt_pk_bf16_f32 v101, v102, v103
	v_cvt_pk_bf16_f32 v102, v104, v105
	v_cvt_pk_bf16_f32 v103, v106, v107
	v_cvt_pk_bf16_f32 v104, v108, v109
	v_cvt_pk_bf16_f32 v105, v110, v111
	v_cvt_pk_bf16_f32 v106, v112, v113
	v_cvt_pk_bf16_f32 v107, v114, v115
	s_add_u32 s50, s56, 0x400000
	s_addc_u32 s51, s57, 0
	global_store_dwordx4 v83, v[100:103], s[50:51]
	global_store_dwordx4 v83, v[104:107], s[50:51] offset:1024
	s_add_u32 s40, s97, s48
	s_addc_u32 s41, s3, 0
	s_add_u32 s40, s40, 0x2000000
	s_addc_u32 s41, s41, 0
	s_add_u32 s42, s54, 0x24000
	s_addc_u32 s43, s55, 0
	s_add_u32 s44, s42, 0x1000
	s_addc_u32 s45, s43, 0
	global_load_dwordx4 v[100:103], v82, s[40:41]
	global_load_dwordx4 v[104:107], v82, s[40:41] offset:16
	global_load_dwordx4 v[108:111], v82, s[40:41] offset:2048
	global_load_dwordx4 v[112:115], v82, s[40:41] offset:2064
	global_load_dwordx4 v[116:119], v82, s[44:45]
	global_load_dwordx4 v[120:123], v82, s[44:45] offset:16
	global_load_dwordx4 v[124:127], v82, s[44:45] offset:2048
	global_load_dwordx4 v[128:131], v82, s[44:45] offset:2064
	global_load_dwordx4 v[132:135], v82, s[42:43]
	global_load_dwordx4 v[136:139], v82, s[42:43] offset:16
	global_load_dwordx4 v[140:143], v82, s[42:43] offset:2048
	global_load_dwordx4 v[144:147], v82, s[42:43] offset:2064
	s_waitcnt vmcnt(28)
	v_pk_mul_f32 v[54:55], v[148:149], v[148:149]
	v_pk_mul_f32 v[56:57], v[150:151], v[150:151]
	v_pk_fma_f32 v[54:55], v[152:153], v[152:153], v[54:55]
	v_pk_fma_f32 v[56:57], v[154:155], v[154:155], v[56:57]
	v_pk_fma_f32 v[54:55], v[156:157], v[156:157], v[54:55]
	v_pk_fma_f32 v[56:57], v[158:159], v[158:159], v[56:57]
	v_pk_fma_f32 v[54:55], v[160:161], v[160:161], v[54:55]
	v_pk_fma_f32 v[56:57], v[162:163], v[162:163], v[56:57]
	v_pk_add_f32 v[54:55], v[54:55], v[56:57]
	v_pk_fma_f32 v[200:201], v[84:85], v[200:201], v[84:85]
	v_add_f32_e32 v54, v54, v55
	v_pk_fma_f32 v[202:203], v[86:87], v[202:203], v[86:87]
	v_pk_fma_f32 v[204:205], v[88:89], v[204:205], v[88:89]
	v_add_f32_dpp v54, v54, v54 quad_perm:[1,0,3,2] row_mask:0xf bank_mask:0xf
	v_pk_fma_f32 v[206:207], v[90:91], v[206:207], v[90:91]
	v_pk_fma_f32 v[208:209], v[92:93], v[208:209], v[92:93]
	v_add_f32_dpp v54, v54, v54 quad_perm:[2,3,0,1] row_mask:0xf bank_mask:0xf
	v_pk_fma_f32 v[210:211], v[94:95], v[210:211], v[94:95]
	v_pk_fma_f32 v[212:213], v[96:97], v[212:213], v[96:97]
	v_add_f32_dpp v54, v54, v54 row_half_mirror row_mask:0xf bank_mask:0xf
	v_pk_fma_f32 v[214:215], v[98:99], v[214:215], v[98:99]
	s_nop 1
	v_add_f32_dpp v54, v54, v54 row_mirror row_mask:0xf bank_mask:0xf
	s_nop 0
	v_mov_b32_e32 v55, v54
	s_nop 1
	v_permlane16_swap_b32_e32 v54, v55
	s_nop 0
	v_add_f32_e32 v54, v54, v55
	s_nop 0
	v_mov_b32_e32 v55, v54
	s_nop 1
	v_permlane32_swap_b32_e32 v54, v55
	s_nop 0
	v_add_f32_e32 v54, v54, v55
	v_fmamk_f32 v54, v54, 0x3a800000, v227
	v_rsq_f32_e32 v54, v54
	s_nop 1
	v_pk_mul_f32 v[148:149], v[148:149], v[54:55] op_sel_hi:[1,0]
	v_pk_mul_f32 v[150:151], v[150:151], v[54:55] op_sel_hi:[1,0]
	v_pk_mul_f32 v[152:153], v[152:153], v[54:55] op_sel_hi:[1,0]
	v_pk_mul_f32 v[154:155], v[154:155], v[54:55] op_sel_hi:[1,0]
	v_pk_mul_f32 v[156:157], v[156:157], v[54:55] op_sel_hi:[1,0]
	v_pk_mul_f32 v[158:159], v[158:159], v[54:55] op_sel_hi:[1,0]
	v_pk_mul_f32 v[160:161], v[160:161], v[54:55] op_sel_hi:[1,0]
	v_pk_mul_f32 v[162:163], v[162:163], v[54:55] op_sel_hi:[1,0]
	v_pk_fma_f32 v[148:149], v[148:149], v[200:201], v[184:185]
	v_pk_fma_f32 v[150:151], v[150:151], v[202:203], v[186:187]
	v_pk_fma_f32 v[152:153], v[152:153], v[204:205], v[188:189]
	v_pk_fma_f32 v[154:155], v[154:155], v[206:207], v[190:191]
	v_pk_fma_f32 v[156:157], v[156:157], v[208:209], v[192:193]
	v_pk_fma_f32 v[158:159], v[158:159], v[210:211], v[194:195]
	v_pk_fma_f32 v[160:161], v[160:161], v[212:213], v[196:197]
	v_pk_fma_f32 v[162:163], v[162:163], v[214:215], v[198:199]
	v_cvt_pk_bf16_f32 v148, v148, v149
	v_cvt_pk_bf16_f32 v149, v150, v151
	v_cvt_pk_bf16_f32 v150, v152, v153
	v_cvt_pk_bf16_f32 v151, v154, v155
	v_cvt_pk_bf16_f32 v152, v156, v157
	v_cvt_pk_bf16_f32 v153, v158, v159
	v_cvt_pk_bf16_f32 v154, v160, v161
	v_cvt_pk_bf16_f32 v155, v162, v163
	s_add_u32 s50, s56, 0x800000
	s_addc_u32 s51, s57, 0
	global_store_dwordx4 v83, v[148:151], s[50:51]
	global_store_dwordx4 v83, v[152:155], s[50:51] offset:1024
	s_add_u32 s40, s97, s48
	s_addc_u32 s41, s3, 0
	s_add_u32 s40, s40, 0x2800000
	s_addc_u32 s41, s41, 0
	s_add_u32 s42, s54, 0x2d000
	s_addc_u32 s43, s55, 0
	s_add_u32 s44, s42, 0x1000
	s_addc_u32 s45, s43, 0
	global_load_dwordx4 v[148:151], v82, s[40:41]
	global_load_dwordx4 v[152:155], v82, s[40:41] offset:16
	global_load_dwordx4 v[156:159], v82, s[40:41] offset:2048
	global_load_dwordx4 v[160:163], v82, s[40:41] offset:2064
	global_load_dwordx4 v[200:203], v82, s[44:45]
	global_load_dwordx4 v[204:207], v82, s[44:45] offset:16
	global_load_dwordx4 v[208:211], v82, s[44:45] offset:2048
	global_load_dwordx4 v[212:215], v82, s[44:45] offset:2064
	global_load_dwordx4 v[184:187], v82, s[42:43]
	global_load_dwordx4 v[188:191], v82, s[42:43] offset:16
	global_load_dwordx4 v[192:195], v82, s[42:43] offset:2048
	global_load_dwordx4 v[196:199], v82, s[42:43] offset:2064
	s_waitcnt vmcnt(28)
	v_pk_mul_f32 v[54:55], v[0:1], v[0:1]
	v_pk_mul_f32 v[56:57], v[2:3], v[2:3]
	v_pk_fma_f32 v[54:55], v[4:5], v[4:5], v[54:55]
	v_pk_fma_f32 v[56:57], v[6:7], v[6:7], v[56:57]
	v_pk_fma_f32 v[54:55], v[8:9], v[8:9], v[54:55]
	v_pk_fma_f32 v[56:57], v[10:11], v[10:11], v[56:57]
	v_pk_fma_f32 v[54:55], v[12:13], v[12:13], v[54:55]
	v_pk_fma_f32 v[56:57], v[14:15], v[14:15], v[56:57]
	v_pk_add_f32 v[54:55], v[54:55], v[56:57]
	v_pk_fma_f32 v[16:17], v[84:85], v[16:17], v[84:85]
	v_add_f32_e32 v54, v54, v55
	v_pk_fma_f32 v[18:19], v[86:87], v[18:19], v[86:87]
	v_pk_fma_f32 v[20:21], v[88:89], v[20:21], v[88:89]
	v_add_f32_dpp v54, v54, v54 quad_perm:[1,0,3,2] row_mask:0xf bank_mask:0xf
	v_pk_fma_f32 v[22:23], v[90:91], v[22:23], v[90:91]
	v_pk_fma_f32 v[24:25], v[92:93], v[24:25], v[92:93]
	v_add_f32_dpp v54, v54, v54 quad_perm:[2,3,0,1] row_mask:0xf bank_mask:0xf
	v_pk_fma_f32 v[26:27], v[94:95], v[26:27], v[94:95]
	v_pk_fma_f32 v[28:29], v[96:97], v[28:29], v[96:97]
	v_add_f32_dpp v54, v54, v54 row_half_mirror row_mask:0xf bank_mask:0xf
	v_pk_fma_f32 v[30:31], v[98:99], v[30:31], v[98:99]
	s_nop 1
	v_add_f32_dpp v54, v54, v54 row_mirror row_mask:0xf bank_mask:0xf
	s_nop 0
	v_mov_b32_e32 v55, v54
	s_nop 1
	v_permlane16_swap_b32_e32 v54, v55
	s_nop 0
	v_add_f32_e32 v54, v54, v55
	s_nop 0
	v_mov_b32_e32 v55, v54
	s_nop 1
	v_permlane32_swap_b32_e32 v54, v55
	s_nop 0
	v_add_f32_e32 v54, v54, v55
	v_fmamk_f32 v54, v54, 0x3a800000, v227
	v_rsq_f32_e32 v54, v54
	s_nop 1
	v_pk_mul_f32 v[0:1], v[0:1], v[54:55] op_sel_hi:[1,0]
	v_pk_mul_f32 v[2:3], v[2:3], v[54:55] op_sel_hi:[1,0]
	v_pk_mul_f32 v[4:5], v[4:5], v[54:55] op_sel_hi:[1,0]
	v_pk_mul_f32 v[6:7], v[6:7], v[54:55] op_sel_hi:[1,0]
	v_pk_mul_f32 v[8:9], v[8:9], v[54:55] op_sel_hi:[1,0]
	v_pk_mul_f32 v[10:11], v[10:11], v[54:55] op_sel_hi:[1,0]
	v_pk_mul_f32 v[12:13], v[12:13], v[54:55] op_sel_hi:[1,0]
	v_pk_mul_f32 v[14:15], v[14:15], v[54:55] op_sel_hi:[1,0]
	v_pk_fma_f32 v[0:1], v[0:1], v[16:17], v[38:39]
	v_pk_fma_f32 v[2:3], v[2:3], v[18:19], v[40:41]
	v_pk_fma_f32 v[4:5], v[4:5], v[20:21], v[42:43]
	v_pk_fma_f32 v[6:7], v[6:7], v[22:23], v[44:45]
	v_pk_fma_f32 v[8:9], v[8:9], v[24:25], v[46:47]
	v_pk_fma_f32 v[10:11], v[10:11], v[26:27], v[48:49]
	v_pk_fma_f32 v[12:13], v[12:13], v[28:29], v[50:51]
	v_pk_fma_f32 v[14:15], v[14:15], v[30:31], v[52:53]
	v_cvt_pk_bf16_f32 v0, v0, v1
	v_cvt_pk_bf16_f32 v1, v2, v3
	v_cvt_pk_bf16_f32 v2, v4, v5
	v_cvt_pk_bf16_f32 v3, v6, v7
	v_cvt_pk_bf16_f32 v4, v8, v9
	v_cvt_pk_bf16_f32 v5, v10, v11
	v_cvt_pk_bf16_f32 v6, v12, v13
	v_cvt_pk_bf16_f32 v7, v14, v15
	s_add_u32 s50, s56, 0xc00000
	s_addc_u32 s51, s57, 0
	global_store_dwordx4 v83, v[0:3], s[50:51]
	global_store_dwordx4 v83, v[4:7], s[50:51] offset:1024
	s_add_u32 s40, s97, s48
	s_addc_u32 s41, s3, 0
	s_add_u32 s40, s40, 0x3000000
	s_addc_u32 s41, s41, 0
	s_add_u32 s42, s54, 0x36000
	s_addc_u32 s43, s55, 0
	s_add_u32 s44, s42, 0x1000
	s_addc_u32 s45, s43, 0
	global_load_dwordx4 v[0:3], v82, s[40:41]
	global_load_dwordx4 v[4:7], v82, s[40:41] offset:16
	global_load_dwordx4 v[8:11], v82, s[40:41] offset:2048
	global_load_dwordx4 v[12:15], v82, s[40:41] offset:2064
	global_load_dwordx4 v[16:19], v82, s[44:45]
	global_load_dwordx4 v[20:23], v82, s[44:45] offset:16
	global_load_dwordx4 v[24:27], v82, s[44:45] offset:2048
	global_load_dwordx4 v[28:31], v82, s[44:45] offset:2064
	global_load_dwordx4 v[38:41], v82, s[42:43]
	global_load_dwordx4 v[42:45], v82, s[42:43] offset:16
	global_load_dwordx4 v[46:49], v82, s[42:43] offset:2048
	global_load_dwordx4 v[50:53], v82, s[42:43] offset:2064
	s_waitcnt vmcnt(28)
	v_pk_mul_f32 v[54:55], v[100:101], v[100:101]
	v_pk_mul_f32 v[56:57], v[102:103], v[102:103]
	v_pk_fma_f32 v[54:55], v[104:105], v[104:105], v[54:55]
	v_pk_fma_f32 v[56:57], v[106:107], v[106:107], v[56:57]
	v_pk_fma_f32 v[54:55], v[108:109], v[108:109], v[54:55]
	v_pk_fma_f32 v[56:57], v[110:111], v[110:111], v[56:57]
	v_pk_fma_f32 v[54:55], v[112:113], v[112:113], v[54:55]
	v_pk_fma_f32 v[56:57], v[114:115], v[114:115], v[56:57]
	v_pk_add_f32 v[54:55], v[54:55], v[56:57]
	v_pk_fma_f32 v[116:117], v[84:85], v[116:117], v[84:85]
	v_add_f32_e32 v54, v54, v55
	v_pk_fma_f32 v[118:119], v[86:87], v[118:119], v[86:87]
	v_pk_fma_f32 v[120:121], v[88:89], v[120:121], v[88:89]
	v_add_f32_dpp v54, v54, v54 quad_perm:[1,0,3,2] row_mask:0xf bank_mask:0xf
	v_pk_fma_f32 v[122:123], v[90:91], v[122:123], v[90:91]
	v_pk_fma_f32 v[124:125], v[92:93], v[124:125], v[92:93]
	v_add_f32_dpp v54, v54, v54 quad_perm:[2,3,0,1] row_mask:0xf bank_mask:0xf
	v_pk_fma_f32 v[126:127], v[94:95], v[126:127], v[94:95]
	v_pk_fma_f32 v[128:129], v[96:97], v[128:129], v[96:97]
	v_add_f32_dpp v54, v54, v54 row_half_mirror row_mask:0xf bank_mask:0xf
	v_pk_fma_f32 v[130:131], v[98:99], v[130:131], v[98:99]
	s_nop 1
	v_add_f32_dpp v54, v54, v54 row_mirror row_mask:0xf bank_mask:0xf
	s_nop 0
	v_mov_b32_e32 v55, v54
	s_nop 1
	v_permlane16_swap_b32_e32 v54, v55
	s_nop 0
	v_add_f32_e32 v54, v54, v55
	s_nop 0
	v_mov_b32_e32 v55, v54
	s_nop 1
	v_permlane32_swap_b32_e32 v54, v55
	s_nop 0
	v_add_f32_e32 v54, v54, v55
	v_fmamk_f32 v54, v54, 0x3a800000, v227
	v_rsq_f32_e32 v54, v54
	s_nop 1
	v_pk_mul_f32 v[100:101], v[100:101], v[54:55] op_sel_hi:[1,0]
	v_pk_mul_f32 v[102:103], v[102:103], v[54:55] op_sel_hi:[1,0]
	v_pk_mul_f32 v[104:105], v[104:105], v[54:55] op_sel_hi:[1,0]
	v_pk_mul_f32 v[106:107], v[106:107], v[54:55] op_sel_hi:[1,0]
	v_pk_mul_f32 v[108:109], v[108:109], v[54:55] op_sel_hi:[1,0]
	v_pk_mul_f32 v[110:111], v[110:111], v[54:55] op_sel_hi:[1,0]
	v_pk_mul_f32 v[112:113], v[112:113], v[54:55] op_sel_hi:[1,0]
	v_pk_mul_f32 v[114:115], v[114:115], v[54:55] op_sel_hi:[1,0]
	v_pk_fma_f32 v[100:101], v[100:101], v[116:117], v[132:133]
	v_pk_fma_f32 v[102:103], v[102:103], v[118:119], v[134:135]
	v_pk_fma_f32 v[104:105], v[104:105], v[120:121], v[136:137]
	v_pk_fma_f32 v[106:107], v[106:107], v[122:123], v[138:139]
	v_pk_fma_f32 v[108:109], v[108:109], v[124:125], v[140:141]
	v_pk_fma_f32 v[110:111], v[110:111], v[126:127], v[142:143]
	v_pk_fma_f32 v[112:113], v[112:113], v[128:129], v[144:145]
	v_pk_fma_f32 v[114:115], v[114:115], v[130:131], v[146:147]
	v_cvt_pk_bf16_f32 v100, v100, v101
	v_cvt_pk_bf16_f32 v101, v102, v103
	v_cvt_pk_bf16_f32 v102, v104, v105
	v_cvt_pk_bf16_f32 v103, v106, v107
	v_cvt_pk_bf16_f32 v104, v108, v109
	v_cvt_pk_bf16_f32 v105, v110, v111
	v_cvt_pk_bf16_f32 v106, v112, v113
	v_cvt_pk_bf16_f32 v107, v114, v115
	s_add_u32 s50, s56, 0x1000000
	s_addc_u32 s51, s57, 0
	global_store_dwordx4 v83, v[100:103], s[50:51]
	global_store_dwordx4 v83, v[104:107], s[50:51] offset:1024
	s_add_u32 s40, s97, s48
	s_addc_u32 s41, s3, 0
	s_add_u32 s40, s40, 0x3800000
	s_addc_u32 s41, s41, 0
	s_add_u32 s42, s54, 0x3f000
	s_addc_u32 s43, s55, 0
	s_add_u32 s44, s42, 0x1000
	s_addc_u32 s45, s43, 0
	global_load_dwordx4 v[100:103], v82, s[40:41]
	global_load_dwordx4 v[104:107], v82, s[40:41] offset:16
	global_load_dwordx4 v[108:111], v82, s[40:41] offset:2048
	global_load_dwordx4 v[112:115], v82, s[40:41] offset:2064
	global_load_dwordx4 v[116:119], v82, s[44:45]
	global_load_dwordx4 v[120:123], v82, s[44:45] offset:16
	global_load_dwordx4 v[124:127], v82, s[44:45] offset:2048
	global_load_dwordx4 v[128:131], v82, s[44:45] offset:2064
	global_load_dwordx4 v[132:135], v82, s[42:43]
	global_load_dwordx4 v[136:139], v82, s[42:43] offset:16
	global_load_dwordx4 v[140:143], v82, s[42:43] offset:2048
	global_load_dwordx4 v[144:147], v82, s[42:43] offset:2064
	s_waitcnt vmcnt(28)
	v_pk_mul_f32 v[54:55], v[148:149], v[148:149]
	v_pk_mul_f32 v[56:57], v[150:151], v[150:151]
	v_pk_fma_f32 v[54:55], v[152:153], v[152:153], v[54:55]
	v_pk_fma_f32 v[56:57], v[154:155], v[154:155], v[56:57]
	v_pk_fma_f32 v[54:55], v[156:157], v[156:157], v[54:55]
	v_pk_fma_f32 v[56:57], v[158:159], v[158:159], v[56:57]
	v_pk_fma_f32 v[54:55], v[160:161], v[160:161], v[54:55]
	v_pk_fma_f32 v[56:57], v[162:163], v[162:163], v[56:57]
	v_pk_add_f32 v[54:55], v[54:55], v[56:57]
	v_pk_fma_f32 v[200:201], v[84:85], v[200:201], v[84:85]
	v_add_f32_e32 v54, v54, v55
	v_pk_fma_f32 v[202:203], v[86:87], v[202:203], v[86:87]
	v_pk_fma_f32 v[204:205], v[88:89], v[204:205], v[88:89]
	v_add_f32_dpp v54, v54, v54 quad_perm:[1,0,3,2] row_mask:0xf bank_mask:0xf
	v_pk_fma_f32 v[206:207], v[90:91], v[206:207], v[90:91]
	v_pk_fma_f32 v[208:209], v[92:93], v[208:209], v[92:93]
	v_add_f32_dpp v54, v54, v54 quad_perm:[2,3,0,1] row_mask:0xf bank_mask:0xf
	v_pk_fma_f32 v[210:211], v[94:95], v[210:211], v[94:95]
	v_pk_fma_f32 v[212:213], v[96:97], v[212:213], v[96:97]
	v_add_f32_dpp v54, v54, v54 row_half_mirror row_mask:0xf bank_mask:0xf
	v_pk_fma_f32 v[214:215], v[98:99], v[214:215], v[98:99]
	s_nop 1
	v_add_f32_dpp v54, v54, v54 row_mirror row_mask:0xf bank_mask:0xf
	s_nop 0
	v_mov_b32_e32 v55, v54
	s_nop 1
	v_permlane16_swap_b32_e32 v54, v55
	s_nop 0
	v_add_f32_e32 v54, v54, v55
	s_nop 0
	v_mov_b32_e32 v55, v54
	s_nop 1
	v_permlane32_swap_b32_e32 v54, v55
	s_nop 0
	v_add_f32_e32 v54, v54, v55
	v_fmamk_f32 v54, v54, 0x3a800000, v227
	v_rsq_f32_e32 v54, v54
	s_nop 1
	v_pk_mul_f32 v[148:149], v[148:149], v[54:55] op_sel_hi:[1,0]
	v_pk_mul_f32 v[150:151], v[150:151], v[54:55] op_sel_hi:[1,0]
	v_pk_mul_f32 v[152:153], v[152:153], v[54:55] op_sel_hi:[1,0]
	v_pk_mul_f32 v[154:155], v[154:155], v[54:55] op_sel_hi:[1,0]
	v_pk_mul_f32 v[156:157], v[156:157], v[54:55] op_sel_hi:[1,0]
	v_pk_mul_f32 v[158:159], v[158:159], v[54:55] op_sel_hi:[1,0]
	v_pk_mul_f32 v[160:161], v[160:161], v[54:55] op_sel_hi:[1,0]
	v_pk_mul_f32 v[162:163], v[162:163], v[54:55] op_sel_hi:[1,0]
	v_pk_fma_f32 v[148:149], v[148:149], v[200:201], v[184:185]
	v_pk_fma_f32 v[150:151], v[150:151], v[202:203], v[186:187]
	v_pk_fma_f32 v[152:153], v[152:153], v[204:205], v[188:189]
	v_pk_fma_f32 v[154:155], v[154:155], v[206:207], v[190:191]
	v_pk_fma_f32 v[156:157], v[156:157], v[208:209], v[192:193]
	v_pk_fma_f32 v[158:159], v[158:159], v[210:211], v[194:195]
	v_pk_fma_f32 v[160:161], v[160:161], v[212:213], v[196:197]
	v_pk_fma_f32 v[162:163], v[162:163], v[214:215], v[198:199]
	v_cvt_pk_bf16_f32 v148, v148, v149
	v_cvt_pk_bf16_f32 v149, v150, v151
	v_cvt_pk_bf16_f32 v150, v152, v153
	v_cvt_pk_bf16_f32 v151, v154, v155
	v_cvt_pk_bf16_f32 v152, v156, v157
	v_cvt_pk_bf16_f32 v153, v158, v159
	v_cvt_pk_bf16_f32 v154, v160, v161
	v_cvt_pk_bf16_f32 v155, v162, v163
	s_add_u32 s50, s56, 0x1400000
	s_addc_u32 s51, s57, 0
	global_store_dwordx4 v83, v[148:151], s[50:51]
	global_store_dwordx4 v83, v[152:155], s[50:51] offset:1024
	s_add_u32 s40, s28, s48
	s_addc_u32 s41, s2, 0
	s_add_u32 s42, s54, 0x48000
	s_addc_u32 s43, s55, 0
	s_add_u32 s44, s42, 0x1000
	s_addc_u32 s45, s43, 0
	global_load_dwordx4 v[148:151], v82, s[40:41]
	global_load_dwordx4 v[152:155], v82, s[40:41] offset:16
	global_load_dwordx4 v[156:159], v82, s[40:41] offset:2048
	global_load_dwordx4 v[160:163], v82, s[40:41] offset:2064
	global_load_dwordx4 v[200:203], v82, s[44:45]
	global_load_dwordx4 v[204:207], v82, s[44:45] offset:16
	global_load_dwordx4 v[208:211], v82, s[44:45] offset:2048
	global_load_dwordx4 v[212:215], v82, s[44:45] offset:2064
	global_load_dwordx4 v[184:187], v82, s[42:43]
	global_load_dwordx4 v[188:191], v82, s[42:43] offset:16
	global_load_dwordx4 v[192:195], v82, s[42:43] offset:2048
	global_load_dwordx4 v[196:199], v82, s[42:43] offset:2064
	s_waitcnt vmcnt(28)
	v_pk_mul_f32 v[54:55], v[0:1], v[0:1]
	v_pk_mul_f32 v[56:57], v[2:3], v[2:3]
	v_pk_fma_f32 v[54:55], v[4:5], v[4:5], v[54:55]
	v_pk_fma_f32 v[56:57], v[6:7], v[6:7], v[56:57]
	v_pk_fma_f32 v[54:55], v[8:9], v[8:9], v[54:55]
	v_pk_fma_f32 v[56:57], v[10:11], v[10:11], v[56:57]
	v_pk_fma_f32 v[54:55], v[12:13], v[12:13], v[54:55]
	v_pk_fma_f32 v[56:57], v[14:15], v[14:15], v[56:57]
	v_pk_add_f32 v[54:55], v[54:55], v[56:57]
	v_pk_fma_f32 v[16:17], v[84:85], v[16:17], v[84:85]
	v_add_f32_e32 v54, v54, v55
	v_pk_fma_f32 v[18:19], v[86:87], v[18:19], v[86:87]
	v_pk_fma_f32 v[20:21], v[88:89], v[20:21], v[88:89]
	v_add_f32_dpp v54, v54, v54 quad_perm:[1,0,3,2] row_mask:0xf bank_mask:0xf
	v_pk_fma_f32 v[22:23], v[90:91], v[22:23], v[90:91]
	v_pk_fma_f32 v[24:25], v[92:93], v[24:25], v[92:93]
	v_add_f32_dpp v54, v54, v54 quad_perm:[2,3,0,1] row_mask:0xf bank_mask:0xf
	v_pk_fma_f32 v[26:27], v[94:95], v[26:27], v[94:95]
	v_pk_fma_f32 v[28:29], v[96:97], v[28:29], v[96:97]
	v_add_f32_dpp v54, v54, v54 row_half_mirror row_mask:0xf bank_mask:0xf
	v_pk_fma_f32 v[30:31], v[98:99], v[30:31], v[98:99]
	s_nop 1
	v_add_f32_dpp v54, v54, v54 row_mirror row_mask:0xf bank_mask:0xf
	s_nop 0
	v_mov_b32_e32 v55, v54
	s_nop 1
	v_permlane16_swap_b32_e32 v54, v55
	s_nop 0
	v_add_f32_e32 v54, v54, v55
	s_nop 0
	v_mov_b32_e32 v55, v54
	s_nop 1
	v_permlane32_swap_b32_e32 v54, v55
	s_nop 0
	v_add_f32_e32 v54, v54, v55
	v_fmamk_f32 v54, v54, 0x3a800000, v227
	v_rsq_f32_e32 v54, v54
	s_nop 1
	v_pk_mul_f32 v[0:1], v[0:1], v[54:55] op_sel_hi:[1,0]
	v_pk_mul_f32 v[2:3], v[2:3], v[54:55] op_sel_hi:[1,0]
	v_pk_mul_f32 v[4:5], v[4:5], v[54:55] op_sel_hi:[1,0]
	v_pk_mul_f32 v[6:7], v[6:7], v[54:55] op_sel_hi:[1,0]
	v_pk_mul_f32 v[8:9], v[8:9], v[54:55] op_sel_hi:[1,0]
	v_pk_mul_f32 v[10:11], v[10:11], v[54:55] op_sel_hi:[1,0]
	v_pk_mul_f32 v[12:13], v[12:13], v[54:55] op_sel_hi:[1,0]
	v_pk_mul_f32 v[14:15], v[14:15], v[54:55] op_sel_hi:[1,0]
	v_pk_fma_f32 v[0:1], v[0:1], v[16:17], v[38:39]
	v_pk_fma_f32 v[2:3], v[2:3], v[18:19], v[40:41]
	v_pk_fma_f32 v[4:5], v[4:5], v[20:21], v[42:43]
	v_pk_fma_f32 v[6:7], v[6:7], v[22:23], v[44:45]
	v_pk_fma_f32 v[8:9], v[8:9], v[24:25], v[46:47]
	v_pk_fma_f32 v[10:11], v[10:11], v[26:27], v[48:49]
	v_pk_fma_f32 v[12:13], v[12:13], v[28:29], v[50:51]
	v_pk_fma_f32 v[14:15], v[14:15], v[30:31], v[52:53]
	v_cvt_pk_bf16_f32 v0, v0, v1
	v_cvt_pk_bf16_f32 v1, v2, v3
	v_cvt_pk_bf16_f32 v2, v4, v5
	v_cvt_pk_bf16_f32 v3, v6, v7
	v_cvt_pk_bf16_f32 v4, v8, v9
	v_cvt_pk_bf16_f32 v5, v10, v11
	v_cvt_pk_bf16_f32 v6, v12, v13
	v_cvt_pk_bf16_f32 v7, v14, v15
	s_add_u32 s50, s56, 0x1800000
	s_addc_u32 s51, s57, 0
	global_store_dwordx4 v83, v[0:3], s[50:51]
	global_store_dwordx4 v83, v[4:7], s[50:51] offset:1024
	s_waitcnt vmcnt(16)
	v_pk_mul_f32 v[54:55], v[100:101], v[100:101]
	v_pk_mul_f32 v[56:57], v[102:103], v[102:103]
	v_pk_fma_f32 v[54:55], v[104:105], v[104:105], v[54:55]
	v_pk_fma_f32 v[56:57], v[106:107], v[106:107], v[56:57]
	v_pk_fma_f32 v[54:55], v[108:109], v[108:109], v[54:55]
	v_pk_fma_f32 v[56:57], v[110:111], v[110:111], v[56:57]
	v_pk_fma_f32 v[54:55], v[112:113], v[112:113], v[54:55]
	v_pk_fma_f32 v[56:57], v[114:115], v[114:115], v[56:57]
	v_pk_add_f32 v[54:55], v[54:55], v[56:57]
	v_pk_fma_f32 v[116:117], v[84:85], v[116:117], v[84:85]
	v_add_f32_e32 v54, v54, v55
	v_pk_fma_f32 v[118:119], v[86:87], v[118:119], v[86:87]
	v_pk_fma_f32 v[120:121], v[88:89], v[120:121], v[88:89]
	v_add_f32_dpp v54, v54, v54 quad_perm:[1,0,3,2] row_mask:0xf bank_mask:0xf
	v_pk_fma_f32 v[122:123], v[90:91], v[122:123], v[90:91]
	v_pk_fma_f32 v[124:125], v[92:93], v[124:125], v[92:93]
	v_add_f32_dpp v54, v54, v54 quad_perm:[2,3,0,1] row_mask:0xf bank_mask:0xf
	v_pk_fma_f32 v[126:127], v[94:95], v[126:127], v[94:95]
	v_pk_fma_f32 v[128:129], v[96:97], v[128:129], v[96:97]
	v_add_f32_dpp v54, v54, v54 row_half_mirror row_mask:0xf bank_mask:0xf
	v_pk_fma_f32 v[130:131], v[98:99], v[130:131], v[98:99]
	s_nop 1
	v_add_f32_dpp v54, v54, v54 row_mirror row_mask:0xf bank_mask:0xf
	s_nop 0
	v_mov_b32_e32 v55, v54
	s_nop 1
	v_permlane16_swap_b32_e32 v54, v55
	s_nop 0
	v_add_f32_e32 v54, v54, v55
	s_nop 0
	v_mov_b32_e32 v55, v54
	s_nop 1
	v_permlane32_swap_b32_e32 v54, v55
	s_nop 0
	v_add_f32_e32 v54, v54, v55
	v_fmamk_f32 v54, v54, 0x3a800000, v227
	v_rsq_f32_e32 v54, v54
	s_nop 1
	v_pk_mul_f32 v[100:101], v[100:101], v[54:55] op_sel_hi:[1,0]
	v_pk_mul_f32 v[102:103], v[102:103], v[54:55] op_sel_hi:[1,0]
	v_pk_mul_f32 v[104:105], v[104:105], v[54:55] op_sel_hi:[1,0]
	v_pk_mul_f32 v[106:107], v[106:107], v[54:55] op_sel_hi:[1,0]
	v_pk_mul_f32 v[108:109], v[108:109], v[54:55] op_sel_hi:[1,0]
	v_pk_mul_f32 v[110:111], v[110:111], v[54:55] op_sel_hi:[1,0]
	v_pk_mul_f32 v[112:113], v[112:113], v[54:55] op_sel_hi:[1,0]
	v_pk_mul_f32 v[114:115], v[114:115], v[54:55] op_sel_hi:[1,0]
	v_pk_fma_f32 v[100:101], v[100:101], v[116:117], v[132:133]
	v_pk_fma_f32 v[102:103], v[102:103], v[118:119], v[134:135]
	v_pk_fma_f32 v[104:105], v[104:105], v[120:121], v[136:137]
	v_pk_fma_f32 v[106:107], v[106:107], v[122:123], v[138:139]
	v_pk_fma_f32 v[108:109], v[108:109], v[124:125], v[140:141]
	v_pk_fma_f32 v[110:111], v[110:111], v[126:127], v[142:143]
	v_pk_fma_f32 v[112:113], v[112:113], v[128:129], v[144:145]
	v_pk_fma_f32 v[114:115], v[114:115], v[130:131], v[146:147]
	v_cvt_pk_bf16_f32 v100, v100, v101
	v_cvt_pk_bf16_f32 v101, v102, v103
	v_cvt_pk_bf16_f32 v102, v104, v105
	v_cvt_pk_bf16_f32 v103, v106, v107
	v_cvt_pk_bf16_f32 v104, v108, v109
	v_cvt_pk_bf16_f32 v105, v110, v111
	v_cvt_pk_bf16_f32 v106, v112, v113
	v_cvt_pk_bf16_f32 v107, v114, v115
	s_add_u32 s50, s56, 0x1c00000
	s_addc_u32 s51, s57, 0
	global_store_dwordx4 v83, v[100:103], s[50:51]
	global_store_dwordx4 v83, v[104:107], s[50:51] offset:1024
	s_waitcnt vmcnt(4)
	v_pk_mul_f32 v[54:55], v[148:149], v[148:149]
	v_pk_mul_f32 v[56:57], v[150:151], v[150:151]
	v_pk_fma_f32 v[54:55], v[152:153], v[152:153], v[54:55]
	v_pk_fma_f32 v[56:57], v[154:155], v[154:155], v[56:57]
	v_pk_fma_f32 v[54:55], v[156:157], v[156:157], v[54:55]
	v_pk_fma_f32 v[56:57], v[158:159], v[158:159], v[56:57]
	v_pk_fma_f32 v[54:55], v[160:161], v[160:161], v[54:55]
	v_pk_fma_f32 v[56:57], v[162:163], v[162:163], v[56:57]
	v_pk_add_f32 v[54:55], v[54:55], v[56:57]
	v_pk_fma_f32 v[200:201], v[84:85], v[200:201], v[84:85]
	v_add_f32_e32 v54, v54, v55
	v_pk_fma_f32 v[202:203], v[86:87], v[202:203], v[86:87]
	v_pk_fma_f32 v[204:205], v[88:89], v[204:205], v[88:89]
	v_add_f32_dpp v54, v54, v54 quad_perm:[1,0,3,2] row_mask:0xf bank_mask:0xf
	v_pk_fma_f32 v[206:207], v[90:91], v[206:207], v[90:91]
	v_pk_fma_f32 v[208:209], v[92:93], v[208:209], v[92:93]
	v_add_f32_dpp v54, v54, v54 quad_perm:[2,3,0,1] row_mask:0xf bank_mask:0xf
	v_pk_fma_f32 v[210:211], v[94:95], v[210:211], v[94:95]
	v_pk_fma_f32 v[212:213], v[96:97], v[212:213], v[96:97]
	v_add_f32_dpp v54, v54, v54 row_half_mirror row_mask:0xf bank_mask:0xf
	v_pk_fma_f32 v[214:215], v[98:99], v[214:215], v[98:99]
	s_nop 1
	v_add_f32_dpp v54, v54, v54 row_mirror row_mask:0xf bank_mask:0xf
	s_nop 0
	v_mov_b32_e32 v55, v54
	s_nop 1
	v_permlane16_swap_b32_e32 v54, v55
	s_nop 0
	v_add_f32_e32 v54, v54, v55
	s_nop 0
	v_mov_b32_e32 v55, v54
	s_nop 1
	v_permlane32_swap_b32_e32 v54, v55
	s_nop 0
	v_add_f32_e32 v54, v54, v55
	v_fmamk_f32 v54, v54, 0x3a800000, v227
	v_rsq_f32_e32 v54, v54
	s_nop 1
	v_pk_mul_f32 v[148:149], v[148:149], v[54:55] op_sel_hi:[1,0]
	v_pk_mul_f32 v[150:151], v[150:151], v[54:55] op_sel_hi:[1,0]
	v_pk_mul_f32 v[152:153], v[152:153], v[54:55] op_sel_hi:[1,0]
	v_pk_mul_f32 v[154:155], v[154:155], v[54:55] op_sel_hi:[1,0]
	v_pk_mul_f32 v[156:157], v[156:157], v[54:55] op_sel_hi:[1,0]
	v_pk_mul_f32 v[158:159], v[158:159], v[54:55] op_sel_hi:[1,0]
	v_pk_mul_f32 v[160:161], v[160:161], v[54:55] op_sel_hi:[1,0]
	v_pk_mul_f32 v[162:163], v[162:163], v[54:55] op_sel_hi:[1,0]
	v_pk_fma_f32 v[148:149], v[148:149], v[200:201], v[184:185]
	v_pk_fma_f32 v[150:151], v[150:151], v[202:203], v[186:187]
	v_pk_fma_f32 v[152:153], v[152:153], v[204:205], v[188:189]
	v_pk_fma_f32 v[154:155], v[154:155], v[206:207], v[190:191]
	v_pk_fma_f32 v[156:157], v[156:157], v[208:209], v[192:193]
	v_pk_fma_f32 v[158:159], v[158:159], v[210:211], v[194:195]
	v_pk_fma_f32 v[160:161], v[160:161], v[212:213], v[196:197]
	v_pk_fma_f32 v[162:163], v[162:163], v[214:215], v[198:199]
	v_cvt_pk_bf16_f32 v148, v148, v149
	v_cvt_pk_bf16_f32 v149, v150, v151
	v_cvt_pk_bf16_f32 v150, v152, v153
	v_cvt_pk_bf16_f32 v151, v154, v155
	v_cvt_pk_bf16_f32 v152, v156, v157
	v_cvt_pk_bf16_f32 v153, v158, v159
	v_cvt_pk_bf16_f32 v154, v160, v161
	v_cvt_pk_bf16_f32 v155, v162, v163
	s_add_u32 s50, s56, 0x2000000
	s_addc_u32 s51, s57, 0
	global_store_dwordx4 v83, v[148:151], s[50:51]
	global_store_dwordx4 v83, v[152:155], s[50:51] offset:1024
